# prologue: second-round weight-transpose items moved from the first 288 waves (which also do rope/S5 tables) to the last 288 waves
# speedup vs baseline: 1.0247x; 1.0059x over previous
; __device__ __forceinline__ void prologue(const Args& a, LAS unsigned char* lds, int vcu, int G, int wave, int lane) {
;     ...
;     for (int it = gw; it < NITEMS; it += NGW) {
;         int r = it; const int l = r / (I_IN + I_OUT + I_GLU); r -= l * (I_IN + I_OUT + I_GLU);
;         if (r < I_IN) { p0_transpose_item(a.in[2] + (size_t)l * D * DIN, D, DIN, (bf16*)(ws + WS_WIN) + (size_t)l * DIN * D, scr, r, lane, a.in[1] + (size_t)l * D); continue; } r -= I_IN;
;         if (r < I_OUT) { p0_transpose_item(a.in[3] + (size_t)l * D * D, D, D, (bf16*)(ws + WS_WOUT) + (size_t)l * D * D, scr, r, lane); continue; } r -= I_OUT;
;         p0_transpose_item(a.in[14] + (size_t)l * 65536, 256, 256, (bf16*)(ws + WS_GLU) + (size_t)l * 65536, scr, r, lane);
;     }
.LBB0_13:
	s_cmpk_gt_i32 s84, 0x7ff
	s_cbranch_scc1 .LBB0_53
	s_sub_i32 s84, 0xfff, s84
	s_lshl_b32 s83, s84, 6
	s_lshl_b32 s57, s84, 4
	s_lshl_b32 s59, s84, 2
	s_cmpk_gt_i32 s84, 0x91f
	s_cbranch_scc1 .LBB0_53
